# grid barriers 2..15 rewritten by hand: per-XCD arrival counter picks the XCD's last arriver (one L2 writeback), every workgroup polls the cross-XCD counter directly (no TOPGEN/XGEN hops)
# speedup vs baseline: 1.0404x; 1.0048x over previous
.LBB0_15:
	s_load_dwordx16 s[16:31], s[0:1], 0x0
	s_load_dwordx16 s[36:51], s[0:1], 0x40
	v_cmp_eq_u32_e64 s[2:3], 0, v128
	s_waitcnt lgkmcnt(0)
	v_writelane_b32 v235, s36, 1
	s_nop 1
	v_writelane_b32 v235, s37, 2
	v_writelane_b32 v235, s38, 3
	v_writelane_b32 v235, s39, 4
	v_writelane_b32 v235, s40, 5
	v_writelane_b32 v235, s41, 6
	v_writelane_b32 v235, s42, 7
	v_writelane_b32 v235, s43, 8
	v_writelane_b32 v235, s44, 9
	v_writelane_b32 v235, s45, 10
	v_writelane_b32 v235, s46, 11
	v_writelane_b32 v235, s47, 12
	v_writelane_b32 v235, s48, 13
	v_writelane_b32 v235, s49, 14
	v_writelane_b32 v235, s50, 15
	v_writelane_b32 v235, s51, 16
	s_load_dwordx16 s[36:51], s[0:1], 0x80
	s_mov_b64 s[0:1], exec
	v_writelane_b32 v235, s2, 17
	s_nop 1
	v_writelane_b32 v235, s3, 18
	v_writelane_b32 v235, 0, 63
	s_and_b64 s[2:3], s[0:1], s[2:3]
	s_mov_b64 exec, s[2:3]
	s_cbranch_execz .LBB0_17
	s_add_i32 s2, 0, 0x23ff0
	v_mov_b32_e32 v0, 0
	v_mov_b32_e32 v1, s2
	s_add_i32 s2, 0, 0x23ff4
	ds_write_b32 v1, v0
	v_mov_b32_e32 v1, s2
	ds_write_b32 v1, v0

.LBB0_154:
.LBB0_155:
	s_cmp_lt_i32 s92, 2
	s_cselect_b64 s[0:1], -1, 0
	s_cmp_gt_i32 s93, 1
	s_cselect_b64 s[4:5], -1, 0
	s_and_b64 s[4:5], s[0:1], s[4:5]
	s_andn2_b64 vcc, exec, s[4:5]
	s_cbranch_vccnz .LBB0_269
	s_andn2_b64 vcc, exec, s[2:3]
	s_cbranch_vccnz .LBB0_210
	v_readlane_b32 s6, v235, 63
	s_nop 0
	s_add_u32 s6, s6, 1
	s_nop 0
	v_writelane_b32 v235, s6, 63
	s_waitcnt vmcnt(0)
	s_barrier
	s_mov_b64 s[2:3], exec
	v_readlane_b32 s4, v235, 17
	v_readlane_b32 s5, v235, 18
	s_and_b64 s[4:5], s[2:3], s[4:5]
	s_mov_b64 exec, s[4:5]
	s_cbranch_execz .LBB0_209
	s_add_i32 s4, 0, 0x23ff0
	v_mov_b32_e32 v0, s4
	s_waitcnt vmcnt(0) expcnt(0) lgkmcnt(0)
	ds_read_b32 v2, v0
	s_add_i32 s4, 0, 0x23ff4
	v_mov_b32_e32 v0, s4
	ds_read_b32 v0, v0
	s_waitcnt lgkmcnt(1)
	v_cmp_ne_u32_e32 vcc, 0, v2
	s_cbranch_vccnz .LBB0_173
	v_readlane_b32 s4, v235, 0
	s_mul_i32 s28, s95, s4
	s_add_u32 s4, s50, 0x1000
	s_addc_u32 s5, s51, 0
	s_add_u32 s6, s50, 0x1100
	s_addc_u32 s7, s51, 0
	s_add_u32 s8, s50, 0x1200
	s_addc_u32 s9, s51, 0
	s_add_u32 s10, s50, 0x1300
	s_mul_i32 s28, s28, s94
	s_addc_u32 s11, s51, 0
	s_mov_b32 s29, 1
	v_mov_b32_e32 v16, 0
	s_branch .LBB0_161

.LBB0_269:
	s_cmp_lt_i32 s92, 3
	s_cselect_b64 s[6:7], -1, 0
	s_cmp_gt_i32 s93, 2
	s_cselect_b64 s[2:3], -1, 0
	s_and_b64 s[2:3], s[6:7], s[2:3]
	s_andn2_b64 vcc, exec, s[2:3]
	s_cbranch_vccnz .LBB0_330
	s_andn2_b64 vcc, exec, s[0:1]
	s_cbranch_vccnz .LBB0_324
	s_waitcnt vmcnt(0)
	s_barrier
	v_readlane_b32 s4, v235, 63
	s_nop 0
	s_add_u32 s4, s4, 1
	s_nop 0
	v_writelane_b32 v235, s4, 63
	s_mov_b64 s[0:1], exec
	v_readlane_b32 s2, v235, 17
	v_readlane_b32 s3, v235, 18
	s_nop 0
	s_and_b64 s[2:3], s[0:1], s[2:3]
	s_mov_b64 exec, s[2:3]
	s_cbranch_execz .LFB_done_k2
	v_mov_b32_e32 v0, 0x23ff0
	ds_read_b32 v2, v0
	ds_read_b32 v3, v0 offset:4
	s_lshl_b32 s2, s96, 8
	s_add_u32 s2, s50, s2
	s_addc_u32 s3, s51, 0
	v_mov_b32_e32 v0, 0x1400
	v_mov_b32_e32 v1, 1
	global_atomic_add v1, v0, v1, s[2:3] sc0
	v_mov_b32_e32 v0, 0x3400
	s_waitcnt vmcnt(0) lgkmcnt(0)
	v_readfirstlane_b32 s5, v1
	v_readfirstlane_b32 s8, v2
	v_readfirstlane_b32 s9, v3
	s_nop 0
	s_add_u32 s5, s5, 1
	s_mul_i32 s8, s8, s4
	s_mul_i32 s4, s9, s4
	s_cmp_lg_u32 s5, s8
	s_mov_b32 s9, 0
	s_cbranch_scc1 .LFB_spin_k2
	buffer_wbl2 sc1
	v_mov_b32_e32 v1, 1
	s_waitcnt vmcnt(0)
	global_atomic_add v0, v1, s[50:51]
.LFB_spin_k2:
	global_load_dword v2, v0, s[50:51] sc1
	s_add_u32 s9, s9, 1
	s_waitcnt vmcnt(0)
	v_readfirstlane_b32 s5, v2
	s_nop 0
	s_cmp_ge_u32 s5, s4
	s_cbranch_scc1 .LFB_rel_k2
	s_sleep 1
	s_cmp_lt_u32 s9, 0x40000
	s_cbranch_scc1 .LFB_spin_k2

.LFB_done_k2:
	s_mov_b64 exec, s[0:1]
	s_barrier

.LBB0_330:
	s_cmp_lt_i32 s92, 4
	s_cselect_b64 s[2:3], -1, 0
	s_cmp_gt_i32 s93, 3
	s_cselect_b64 s[0:1], -1, 0
	s_and_b64 s[0:1], s[2:3], s[0:1]
	s_andn2_b64 vcc, exec, s[0:1]
	s_cbranch_vccnz .LBB0_433
	s_andn2_b64 vcc, exec, s[6:7]
	s_cbranch_vccnz .LBB0_385
	s_waitcnt vmcnt(0)
	s_barrier
	v_readlane_b32 s6, v235, 63
	s_nop 0
	s_add_u32 s6, s6, 1
	s_nop 0
	v_writelane_b32 v235, s6, 63
	s_mov_b64 s[0:1], exec
	v_readlane_b32 s4, v235, 17
	v_readlane_b32 s5, v235, 18
	s_nop 0
	s_and_b64 s[4:5], s[0:1], s[4:5]
	s_mov_b64 exec, s[4:5]
	s_cbranch_execz .LFB_done_k3
	v_mov_b32_e32 v0, 0x23ff0
	ds_read_b32 v2, v0
	ds_read_b32 v3, v0 offset:4
	s_lshl_b32 s4, s96, 8
	s_add_u32 s4, s50, s4
	s_addc_u32 s5, s51, 0
	v_mov_b32_e32 v0, 0x1400
	v_mov_b32_e32 v1, 1
	global_atomic_add v1, v0, v1, s[4:5] sc0
	v_mov_b32_e32 v0, 0x3400
	s_waitcnt vmcnt(0) lgkmcnt(0)
	v_readfirstlane_b32 s7, v1
	v_readfirstlane_b32 s8, v2
	v_readfirstlane_b32 s9, v3
	s_nop 0
	s_add_u32 s7, s7, 1
	s_mul_i32 s8, s8, s6
	s_mul_i32 s6, s9, s6
	s_cmp_lg_u32 s7, s8
	s_mov_b32 s9, 0
	s_cbranch_scc1 .LFB_spin_k3
	buffer_wbl2 sc1
	v_mov_b32_e32 v1, 1
	s_waitcnt vmcnt(0)
	global_atomic_add v0, v1, s[50:51]
.LFB_spin_k3:
	global_load_dword v2, v0, s[50:51] sc1
	s_add_u32 s9, s9, 1
	s_waitcnt vmcnt(0)
	v_readfirstlane_b32 s7, v2
	s_nop 0
	s_cmp_ge_u32 s7, s6
	s_cbranch_scc1 .LFB_rel_k3
	s_sleep 1
	s_cmp_lt_u32 s9, 0x40000
	s_cbranch_scc1 .LFB_spin_k3

.LBB0_433:
	s_cmp_lt_i32 s92, 5
	s_cselect_b64 s[0:1], -1, 0
	s_cmp_gt_i32 s93, 4
	s_cselect_b64 s[4:5], -1, 0
	s_and_b64 s[4:5], s[0:1], s[4:5]
	s_andn2_b64 vcc, exec, s[4:5]
	s_cbranch_vccnz .LBB0_680
	s_andn2_b64 vcc, exec, s[2:3]
	s_cbranch_vccnz .LBB0_488
	s_waitcnt vmcnt(0)
	s_barrier
	v_readlane_b32 s6, v235, 63
	s_nop 0
	s_add_u32 s6, s6, 1
	s_nop 0
	v_writelane_b32 v235, s6, 63
	s_mov_b64 s[2:3], exec
	v_readlane_b32 s4, v235, 17
	v_readlane_b32 s5, v235, 18
	s_nop 0
	s_and_b64 s[4:5], s[2:3], s[4:5]
	s_mov_b64 exec, s[4:5]
	s_cbranch_execz .LFB_done_k4
	v_mov_b32_e32 v0, 0x23ff0
	ds_read_b32 v2, v0
	ds_read_b32 v3, v0 offset:4
	s_lshl_b32 s4, s96, 8
	s_add_u32 s4, s50, s4
	s_addc_u32 s5, s51, 0
	v_mov_b32_e32 v0, 0x1400
	v_mov_b32_e32 v1, 1
	global_atomic_add v1, v0, v1, s[4:5] sc0
	v_mov_b32_e32 v0, 0x3400
	s_waitcnt vmcnt(0) lgkmcnt(0)
	v_readfirstlane_b32 s7, v1
	v_readfirstlane_b32 s8, v2
	v_readfirstlane_b32 s9, v3
	s_nop 0
	s_add_u32 s7, s7, 1
	s_mul_i32 s8, s8, s6
	s_mul_i32 s6, s9, s6
	s_cmp_lg_u32 s7, s8
	s_mov_b32 s9, 0
	s_cbranch_scc1 .LFB_spin_k4
	buffer_wbl2 sc1
	v_mov_b32_e32 v1, 1
	s_waitcnt vmcnt(0)
	global_atomic_add v0, v1, s[50:51]

.LFB_done_k4:
	s_mov_b64 exec, s[2:3]
	s_barrier

.LBB0_680:
	s_cmp_lt_i32 s92, 6
	s_cselect_b64 s[2:3], -1, 0
	s_cmp_gt_i32 s93, 5
	s_cselect_b64 s[4:5], -1, 0
	s_and_b64 s[4:5], s[2:3], s[4:5]
	s_andn2_b64 vcc, exec, s[4:5]
	s_cbranch_vccnz .LBB0_743
	s_andn2_b64 vcc, exec, s[0:1]
	s_cbranch_vccnz .LBB0_735
	s_waitcnt vmcnt(0)
	s_barrier
	v_readlane_b32 s6, v235, 63
	s_nop 0
	s_add_u32 s6, s6, 1
	s_nop 0
	v_writelane_b32 v235, s6, 63
	s_mov_b64 s[0:1], exec
	v_readlane_b32 s4, v235, 17
	v_readlane_b32 s5, v235, 18
	s_nop 0
	s_and_b64 s[4:5], s[0:1], s[4:5]
	s_mov_b64 exec, s[4:5]
	s_cbranch_execz .LFB_done_k5
	v_mov_b32_e32 v0, 0x23ff0
	ds_read_b32 v2, v0
	ds_read_b32 v3, v0 offset:4
	s_lshl_b32 s4, s96, 8
	s_add_u32 s4, s50, s4
	s_addc_u32 s5, s51, 0
	v_mov_b32_e32 v0, 0x1400
	v_mov_b32_e32 v1, 1
	global_atomic_add v1, v0, v1, s[4:5] sc0
	v_mov_b32_e32 v0, 0x3400
	s_waitcnt vmcnt(0) lgkmcnt(0)
	v_readfirstlane_b32 s7, v1
	v_readfirstlane_b32 s8, v2
	v_readfirstlane_b32 s9, v3
	s_nop 0
	s_add_u32 s7, s7, 1
	s_mul_i32 s8, s8, s6
	s_mul_i32 s6, s9, s6
	s_cmp_lg_u32 s7, s8
	s_mov_b32 s9, 0
	s_cbranch_scc1 .LFB_spin_k5
	buffer_wbl2 sc1
	v_mov_b32_e32 v1, 1
	s_waitcnt vmcnt(0)
	global_atomic_add v0, v1, s[50:51]

.LBB0_743:
	s_cmp_lt_i32 s92, 7
	s_cselect_b64 s[6:7], -1, 0
	s_cmp_gt_i32 s93, 6
	s_cselect_b64 s[0:1], -1, 0
	s_and_b64 s[0:1], s[6:7], s[0:1]
	s_andn2_b64 vcc, exec, s[0:1]
	s_cbranch_vccnz .LBB0_916
	s_andn2_b64 vcc, exec, s[2:3]
	s_cbranch_vccnz .LBB0_798
	s_waitcnt vmcnt(0)
	s_barrier
	v_readlane_b32 s4, v235, 63
	s_nop 0
	s_add_u32 s4, s4, 1
	s_nop 0
	v_writelane_b32 v235, s4, 63
	s_mov_b64 s[0:1], exec
	v_readlane_b32 s2, v235, 17
	v_readlane_b32 s3, v235, 18
	s_nop 0
	s_and_b64 s[2:3], s[0:1], s[2:3]
	s_mov_b64 exec, s[2:3]
	s_cbranch_execz .LFB_done_k6
	v_mov_b32_e32 v0, 0x23ff0
	ds_read_b32 v2, v0
	ds_read_b32 v3, v0 offset:4
	s_lshl_b32 s2, s96, 8
	s_add_u32 s2, s50, s2
	s_addc_u32 s3, s51, 0
	v_mov_b32_e32 v0, 0x1400
	v_mov_b32_e32 v1, 1
	global_atomic_add v1, v0, v1, s[2:3] sc0
	v_mov_b32_e32 v0, 0x3400
	s_waitcnt vmcnt(0) lgkmcnt(0)
	v_readfirstlane_b32 s5, v1
	v_readfirstlane_b32 s8, v2
	v_readfirstlane_b32 s9, v3
	s_nop 0
	s_add_u32 s5, s5, 1
	s_mul_i32 s8, s8, s4
	s_mul_i32 s4, s9, s4
	s_cmp_lg_u32 s5, s8
	s_mov_b32 s9, 0
	s_cbranch_scc1 .LFB_spin_k6
	buffer_wbl2 sc1
	v_mov_b32_e32 v1, 1
	s_waitcnt vmcnt(0)
	global_atomic_add v0, v1, s[50:51]

.LBB0_908:
	s_cbranch_execz .LBB0_910
	s_branch .LBB0_916
.LT_entry:
	s_cmp_eq_u32 s64, 0
	s_cbranch_scc1 .LT_job0
	s_cmp_eq_u32 s64, 1
	s_cbranch_scc1 .LT_job1
	s_cmp_eq_u32 s64, 2
	s_cbranch_scc1 .LT_job2
	s_cmp_eq_u32 s64, 3
	s_cbranch_scc1 .LT_job3
	s_cmp_eq_u32 s64, 4
	s_cbranch_scc1 .LT_job4
	s_cmp_eq_u32 s64, 5
	s_cbranch_scc1 .LT_job5
	s_cmp_eq_u32 s64, 6
	s_cbranch_scc1 .LT_job6
	s_cmp_eq_u32 s64, 7
	s_cbranch_scc1 .LT_job7
	s_cmp_eq_u32 s64, 8
	s_cbranch_scc1 .LT_job8

.LT_done:
	s_cmp_eq_u32 s67, 0
	s_cbranch_scc1 .LT_ret0
	s_cmp_eq_u32 s67, 1
	s_cbranch_scc1 .LT_ret1
	s_cmp_eq_u32 s67, 2
	s_cbranch_scc1 .LT_ret2
	s_endpgm
.LBB0_909:
.LBB0_910:
	v_lshrrev_b32_e32 v1, 6, v128
	v_lshl_add_u32 v0, s34, 3, v1
	s_movk_i32 s0, 0x1600
	v_cmp_gt_i32_e32 vcc, s0, v0
	s_and_saveexec_b64 s[0:1], vcc
	s_cbranch_execz .LBB0_915
	s_waitcnt vmcnt(0)
	v_lshlrev_b32_e32 v3, 2, v128
	v_and_b32_e32 v8, 0x7c, v3
	v_lshlrev_b32_e32 v3, 3, v128
	s_movk_i32 s2, 0x2200
	v_bfe_u32 v5, v128, 3, 3
	v_and_b32_e32 v3, 56, v3
	v_mad_u32_u24 v1, v1, s2, 0
	v_mul_u32_u24_e32 v6, 0x84, v3
	v_lshlrev_b32_e32 v7, 2, v5
	v_mov_b32_e32 v9, 0
	v_add_u32_e32 v4, v1, v8
	v_add3_u32 v18, v1, v6, v7
	v_lshl_add_u64 v[6:7], s[44:45], 0, v[8:9]
	v_lshlrev_b32_e32 v8, 1, v3
	v_bfe_u32 v2, v128, 5, 1
	v_lshl_add_u64 v[8:9], s[50:51], 0, v[8:9]
	s_mov_b64 s[2:3], 0x8404000
	s_lshl_b32 s4, s94, 3
	s_movk_i32 s5, 0x84
	v_or_b32_e32 v19, 8, v5
	v_or_b32_e32 v20, 16, v5
	v_or_b32_e32 v21, 24, v5
	v_lshl_add_u64 v[8:9], v[8:9], 0, s[2:3]
	v_mov_b32_e32 v1, v2
	s_mov_b64 s[2:3], 0
	s_mov_b32 s8, 0x2e8ba2e9
	s_movk_i32 s9, 0xff50
	s_movk_i32 s10, 0x5800
	s_movk_i32 s11, 0x80
	s_movk_i32 s12, 0x15ff

.LBB0_916:
	s_cmp_lt_i32 s92, 8
	s_cselect_b64 s[0:1], -1, 0
	s_cmp_gt_i32 s93, 7
	s_cselect_b64 s[2:3], -1, 0
	s_and_b64 s[2:3], s[0:1], s[2:3]
	s_andn2_b64 vcc, exec, s[2:3]
	s_cbranch_vccnz .LBB0_1098
	s_andn2_b64 vcc, exec, s[6:7]
	s_cbranch_vccnz .LBB0_971
	s_waitcnt vmcnt(0)
	s_barrier
	v_readlane_b32 s6, v235, 63
	s_nop 0
	s_add_u32 s6, s6, 1
	s_nop 0
	v_writelane_b32 v235, s6, 63
	s_mov_b64 s[2:3], exec
	v_readlane_b32 s4, v235, 17
	v_readlane_b32 s5, v235, 18
	s_nop 0
	s_and_b64 s[4:5], s[2:3], s[4:5]
	s_mov_b64 exec, s[4:5]
	s_cbranch_execz .LFB_done_k7
	v_mov_b32_e32 v0, 0x23ff0
	ds_read_b32 v2, v0
	ds_read_b32 v3, v0 offset:4
	s_lshl_b32 s4, s96, 8
	s_add_u32 s4, s50, s4
	s_addc_u32 s5, s51, 0
	v_mov_b32_e32 v0, 0x1400
	v_mov_b32_e32 v1, 1
	global_atomic_add v1, v0, v1, s[4:5] sc0
	v_mov_b32_e32 v0, 0x3400
	s_waitcnt vmcnt(0) lgkmcnt(0)
	v_readfirstlane_b32 s7, v1
	v_readfirstlane_b32 s8, v2
	v_readfirstlane_b32 s9, v3
	s_nop 0
	s_add_u32 s7, s7, 1
	s_mul_i32 s8, s8, s6
	s_mul_i32 s6, s9, s6
	s_cmp_lg_u32 s7, s8
	s_mov_b32 s9, 0
	s_cbranch_scc1 .LFB_spin_k7
	buffer_wbl2 sc1
	v_mov_b32_e32 v1, 1
	s_waitcnt vmcnt(0)
	global_atomic_add v0, v1, s[50:51]

.LBB0_1098:
	s_cmp_lt_i32 s92, 9
	s_cselect_b64 s[2:3], -1, 0
	s_cmp_gt_i32 s93, 8
	s_cselect_b64 s[4:5], -1, 0
	s_and_b64 s[4:5], s[2:3], s[4:5]
	s_andn2_b64 vcc, exec, s[4:5]
	s_cbranch_vccnz .LBB0_1157
	s_andn2_b64 vcc, exec, s[0:1]
	s_cbranch_vccnz .LBB0_1153
	s_waitcnt vmcnt(0)
	s_barrier
	v_readlane_b32 s6, v235, 63
	s_nop 0
	s_add_u32 s6, s6, 1
	s_nop 0
	v_writelane_b32 v235, s6, 63
	s_mov_b64 s[0:1], exec
	v_readlane_b32 s4, v235, 17
	v_readlane_b32 s5, v235, 18
	s_nop 0
	s_and_b64 s[4:5], s[0:1], s[4:5]
	s_mov_b64 exec, s[4:5]
	s_cbranch_execz .LFB_done_k8
	v_mov_b32_e32 v0, 0x23ff0
	ds_read_b32 v2, v0
	ds_read_b32 v3, v0 offset:4
	s_lshl_b32 s4, s96, 8
	s_add_u32 s4, s50, s4
	s_addc_u32 s5, s51, 0
	v_mov_b32_e32 v0, 0x1400
	v_mov_b32_e32 v1, 1
	global_atomic_add v1, v0, v1, s[4:5] sc0
	v_mov_b32_e32 v0, 0x3400
	s_waitcnt vmcnt(0) lgkmcnt(0)
	v_readfirstlane_b32 s7, v1
	v_readfirstlane_b32 s8, v2
	v_readfirstlane_b32 s9, v3
	s_nop 0
	s_add_u32 s7, s7, 1
	s_mul_i32 s8, s8, s6
	s_mul_i32 s6, s9, s6
	s_cmp_lg_u32 s7, s8
	s_mov_b32 s9, 0
	s_cbranch_scc1 .LFB_spin_k8
	buffer_wbl2 sc1
	v_mov_b32_e32 v1, 1
	s_waitcnt vmcnt(0)
	global_atomic_add v0, v1, s[50:51]

.LBB0_1157:
	s_cmp_lt_i32 s92, 10
	s_cselect_b64 s[4:5], -1, 0
	s_cmp_gt_i32 s93, 9
	s_cselect_b64 s[0:1], -1, 0
	v_writelane_b32 v235, s4, 19
	s_and_b64 s[0:1], s[4:5], s[0:1]
	s_andn2_b64 vcc, exec, s[0:1]
	v_writelane_b32 v235, s5, 20
	s_cbranch_vccnz .LBB0_1326
	s_andn2_b64 vcc, exec, s[2:3]
	s_cbranch_vccnz .LBB0_1212
	s_waitcnt vmcnt(0)
	s_barrier
	v_readlane_b32 s4, v235, 63
	s_nop 0
	s_add_u32 s4, s4, 1
	s_nop 0
	v_writelane_b32 v235, s4, 63
	s_mov_b64 s[0:1], exec
	v_readlane_b32 s2, v235, 17
	v_readlane_b32 s3, v235, 18
	s_nop 0
	s_and_b64 s[2:3], s[0:1], s[2:3]
	s_mov_b64 exec, s[2:3]
	s_cbranch_execz .LFB_done_k9
	v_mov_b32_e32 v0, 0x23ff0
	ds_read_b32 v2, v0
	ds_read_b32 v3, v0 offset:4
	s_lshl_b32 s2, s96, 8
	s_add_u32 s2, s50, s2
	s_addc_u32 s3, s51, 0
	v_mov_b32_e32 v0, 0x1400
	v_mov_b32_e32 v1, 1
	global_atomic_add v1, v0, v1, s[2:3] sc0
	v_mov_b32_e32 v0, 0x3400
	s_waitcnt vmcnt(0) lgkmcnt(0)
	v_readfirstlane_b32 s5, v1
	v_readfirstlane_b32 s6, v2
	v_readfirstlane_b32 s7, v3
	s_nop 0
	s_add_u32 s5, s5, 1
	s_mul_i32 s6, s6, s4
	s_mul_i32 s4, s7, s4
	s_cmp_lg_u32 s5, s6
	s_mov_b32 s7, 0
	s_cbranch_scc1 .LFB_spin_k9
	buffer_wbl2 sc1
	v_mov_b32_e32 v1, 1
	s_waitcnt vmcnt(0)
	global_atomic_add v0, v1, s[50:51]
.LFB_spin_k9:
	global_load_dword v2, v0, s[50:51] sc1
	s_add_u32 s7, s7, 1
	s_waitcnt vmcnt(0)
	v_readfirstlane_b32 s5, v2
	s_nop 0
	s_cmp_ge_u32 s5, s4
	s_cbranch_scc1 .LFB_rel_k9
	s_sleep 1
	s_cmp_lt_u32 s7, 0x40000
	s_cbranch_scc1 .LFB_spin_k9

.LBB0_1326:
	s_cmp_lt_i32 s92, 11
	s_cselect_b64 s[0:1], -1, 0
	s_cmp_gt_i32 s93, 10
	s_cselect_b64 s[2:3], -1, 0
	s_and_b64 s[2:3], s[0:1], s[2:3]
	s_andn2_b64 vcc, exec, s[2:3]
	s_cbranch_vccnz .LBB0_1493
	v_readlane_b32 s2, v235, 19
	v_readlane_b32 s3, v235, 20
	s_andn2_b64 vcc, exec, s[2:3]
	s_cbranch_vccnz .LBB0_1381
	s_waitcnt vmcnt(0)
	s_barrier
	v_readlane_b32 s6, v235, 63
	s_nop 0
	s_add_u32 s6, s6, 1
	s_nop 0
	v_writelane_b32 v235, s6, 63
	s_mov_b64 s[2:3], exec
	v_readlane_b32 s4, v235, 17
	v_readlane_b32 s5, v235, 18
	s_nop 0
	s_and_b64 s[4:5], s[2:3], s[4:5]
	s_mov_b64 exec, s[4:5]
	s_cbranch_execz .LFB_done_k10
	v_mov_b32_e32 v0, 0x23ff0
	ds_read_b32 v2, v0
	ds_read_b32 v3, v0 offset:4
	s_lshl_b32 s4, s96, 8
	s_add_u32 s4, s50, s4
	s_addc_u32 s5, s51, 0
	v_mov_b32_e32 v0, 0x1400
	v_mov_b32_e32 v1, 1
	global_atomic_add v1, v0, v1, s[4:5] sc0
	v_mov_b32_e32 v0, 0x3400
	s_waitcnt vmcnt(0) lgkmcnt(0)
	v_readfirstlane_b32 s7, v1
	v_readfirstlane_b32 s8, v2
	v_readfirstlane_b32 s9, v3
	s_nop 0
	s_add_u32 s7, s7, 1
	s_mul_i32 s8, s8, s6
	s_mul_i32 s6, s9, s6
	s_cmp_lg_u32 s7, s8
	s_mov_b32 s9, 0
	s_cbranch_scc1 .LFB_spin_k10
	buffer_wbl2 sc1
	v_mov_b32_e32 v1, 1
	s_waitcnt vmcnt(0)
	global_atomic_add v0, v1, s[50:51]

.LBB0_1493:
	s_cmp_lt_i32 s92, 12
	s_cselect_b64 s[2:3], -1, 0
	s_cmp_gt_i32 s93, 11
	s_cselect_b64 s[4:5], -1, 0
	s_and_b64 s[4:5], s[2:3], s[4:5]
	s_andn2_b64 vcc, exec, s[4:5]
	s_cbranch_vccnz .LBB0_1568
	s_andn2_b64 vcc, exec, s[0:1]
	s_cbranch_vccnz .LBB0_1548
	s_waitcnt vmcnt(0)
	s_barrier
	v_readlane_b32 s6, v235, 63
	s_nop 0
	s_add_u32 s6, s6, 1
	s_nop 0
	v_writelane_b32 v235, s6, 63
	s_mov_b64 s[0:1], exec
	v_readlane_b32 s4, v235, 17
	v_readlane_b32 s5, v235, 18
	s_nop 0
	s_and_b64 s[4:5], s[0:1], s[4:5]
	s_mov_b64 exec, s[4:5]
	s_cbranch_execz .LFB_done_k11
	v_mov_b32_e32 v0, 0x23ff0
	ds_read_b32 v2, v0
	ds_read_b32 v3, v0 offset:4
	s_lshl_b32 s4, s96, 8
	s_add_u32 s4, s50, s4
	s_addc_u32 s5, s51, 0
	v_mov_b32_e32 v0, 0x1400
	v_mov_b32_e32 v1, 1
	global_atomic_add v1, v0, v1, s[4:5] sc0
	v_mov_b32_e32 v0, 0x3400
	s_waitcnt vmcnt(0) lgkmcnt(0)
	v_readfirstlane_b32 s7, v1
	v_readfirstlane_b32 s8, v2
	v_readfirstlane_b32 s9, v3
	s_nop 0
	s_add_u32 s7, s7, 1
	s_mul_i32 s8, s8, s6
	s_mul_i32 s6, s9, s6
	s_cmp_lg_u32 s7, s8
	s_mov_b32 s9, 0
	s_cbranch_scc1 .LFB_spin_k11
	buffer_wbl2 sc1
	v_mov_b32_e32 v1, 1
	s_waitcnt vmcnt(0)
	global_atomic_add v0, v1, s[50:51]

.LBB0_1568:
	s_cmp_lt_i32 s92, 13
	s_cselect_b64 s[4:5], -1, 0
	s_cmp_gt_i32 s93, 12
	s_cselect_b64 s[0:1], -1, 0
	s_and_b64 s[0:1], s[4:5], s[0:1]
	s_andn2_b64 vcc, exec, s[0:1]
	s_cbranch_vccnz .LBB0_1627
	s_andn2_b64 vcc, exec, s[2:3]
	s_cbranch_vccnz .LBB0_1623
	s_waitcnt vmcnt(0)
	s_barrier
	v_readlane_b32 s6, v235, 63
	s_nop 0
	s_add_u32 s6, s6, 1
	s_nop 0
	v_writelane_b32 v235, s6, 63
	s_mov_b64 s[0:1], exec
	v_readlane_b32 s2, v235, 17
	v_readlane_b32 s3, v235, 18
	s_nop 0
	s_and_b64 s[2:3], s[0:1], s[2:3]
	s_mov_b64 exec, s[2:3]
	s_cbranch_execz .LFB_done_k12
	v_mov_b32_e32 v0, 0x23ff0
	ds_read_b32 v2, v0
	ds_read_b32 v3, v0 offset:4
	s_lshl_b32 s2, s96, 8
	s_add_u32 s2, s50, s2
	s_addc_u32 s3, s51, 0
	v_mov_b32_e32 v0, 0x1400
	v_mov_b32_e32 v1, 1
	global_atomic_add v1, v0, v1, s[2:3] sc0
	v_mov_b32_e32 v0, 0x3400
	s_waitcnt vmcnt(0) lgkmcnt(0)
	v_readfirstlane_b32 s7, v1
	v_readfirstlane_b32 s8, v2
	v_readfirstlane_b32 s9, v3
	s_nop 0
	s_add_u32 s7, s7, 1
	s_mul_i32 s8, s8, s6
	s_mul_i32 s6, s9, s6
	s_cmp_lg_u32 s7, s8
	s_mov_b32 s9, 0
	s_cbranch_scc1 .LFB_spin_k12
	buffer_wbl2 sc1
	v_mov_b32_e32 v1, 1
	s_waitcnt vmcnt(0)
	global_atomic_add v0, v1, s[50:51]

.LBB0_1627:
	s_cmp_lt_i32 s92, 14
	s_cselect_b64 s[0:1], -1, 0
	s_cmp_gt_i32 s93, 13
	s_cselect_b64 s[2:3], -1, 0
	s_and_b64 s[2:3], s[0:1], s[2:3]
	s_andn2_b64 vcc, exec, s[2:3]
	s_cbranch_vccnz .LBB0_1698
	s_andn2_b64 vcc, exec, s[4:5]
	s_cbranch_vccnz .LBB0_1682
	s_waitcnt vmcnt(0)
	s_barrier
	v_readlane_b32 s6, v235, 63
	s_nop 0
	s_add_u32 s6, s6, 1
	s_nop 0
	v_writelane_b32 v235, s6, 63
	s_mov_b64 s[2:3], exec
	v_readlane_b32 s4, v235, 17
	v_readlane_b32 s5, v235, 18
	s_nop 0
	s_and_b64 s[4:5], s[2:3], s[4:5]
	s_mov_b64 exec, s[4:5]
	s_cbranch_execz .LFB_done_k13
	v_mov_b32_e32 v0, 0x23ff0
	ds_read_b32 v2, v0
	ds_read_b32 v3, v0 offset:4
	s_lshl_b32 s4, s96, 8
	s_add_u32 s4, s50, s4
	s_addc_u32 s5, s51, 0
	v_mov_b32_e32 v0, 0x1400
	v_mov_b32_e32 v1, 1
	global_atomic_add v1, v0, v1, s[4:5] sc0
	v_mov_b32_e32 v0, 0x3400
	s_waitcnt vmcnt(0) lgkmcnt(0)
	v_readfirstlane_b32 s7, v1
	v_readfirstlane_b32 s8, v2
	v_readfirstlane_b32 s9, v3
	s_nop 0
	s_add_u32 s7, s7, 1
	s_mul_i32 s8, s8, s6
	s_mul_i32 s6, s9, s6
	s_cmp_lg_u32 s7, s8
	s_mov_b32 s9, 0
	s_cbranch_scc1 .LFB_spin_k13
	buffer_wbl2 sc1
	v_mov_b32_e32 v1, 1
	s_waitcnt vmcnt(0)
	global_atomic_add v0, v1, s[50:51]

.LBB0_1698:
	s_cmp_lt_i32 s92, 15
	s_cselect_b64 s[2:3], -1, 0
	s_cmp_gt_i32 s93, 14
	s_cselect_b64 s[4:5], -1, 0
	s_and_b64 s[4:5], s[2:3], s[4:5]
	s_andn2_b64 vcc, exec, s[4:5]
	s_cbranch_vccnz .LBB0_1773
	s_andn2_b64 vcc, exec, s[0:1]
	s_cbranch_vccnz .LBB0_1753
	s_waitcnt vmcnt(0)
	s_barrier
	v_readlane_b32 s6, v235, 63
	s_nop 0
	s_add_u32 s6, s6, 1
	s_nop 0
	v_writelane_b32 v235, s6, 63
	s_mov_b64 s[0:1], exec
	v_readlane_b32 s4, v235, 17
	v_readlane_b32 s5, v235, 18
	s_nop 0
	s_and_b64 s[4:5], s[0:1], s[4:5]
	s_mov_b64 exec, s[4:5]
	s_cbranch_execz .LFB_done_k14
	v_mov_b32_e32 v0, 0x23ff0
	ds_read_b32 v2, v0
	ds_read_b32 v3, v0 offset:4
	s_lshl_b32 s4, s96, 8
	s_add_u32 s4, s50, s4
	s_addc_u32 s5, s51, 0
	v_mov_b32_e32 v0, 0x1400
	v_mov_b32_e32 v1, 1
	global_atomic_add v1, v0, v1, s[4:5] sc0
	v_mov_b32_e32 v0, 0x3400
	s_waitcnt vmcnt(0) lgkmcnt(0)
	v_readfirstlane_b32 s7, v1
	v_readfirstlane_b32 s8, v2
	v_readfirstlane_b32 s9, v3
	s_nop 0
	s_add_u32 s7, s7, 1
	s_mul_i32 s8, s8, s6
	s_mul_i32 s6, s9, s6
	s_cmp_lg_u32 s7, s8
	s_mov_b32 s9, 0
	s_cbranch_scc1 .LFB_spin_k14
	buffer_wbl2 sc1
	v_mov_b32_e32 v1, 1
	s_waitcnt vmcnt(0)
	global_atomic_add v0, v1, s[50:51]

.LBB0_1773:
	s_cmp_lt_i32 s92, 16
	s_cselect_b64 s[0:1], -1, 0
	s_cmp_gt_i32 s93, 15
	s_cselect_b64 s[4:5], -1, 0
	s_and_b64 s[0:1], s[0:1], s[4:5]
	s_andn2_b64 vcc, exec, s[0:1]
	s_cbranch_vccnz .LBB0_1831
	s_andn2_b64 vcc, exec, s[2:3]
	s_cbranch_vccnz .LBB0_1828
	s_waitcnt vmcnt(0)
	s_barrier
	v_readlane_b32 s4, v235, 63
	s_nop 0
	s_add_u32 s4, s4, 1
	s_nop 0
	v_writelane_b32 v235, s4, 63
	s_mov_b64 s[0:1], exec
	v_readlane_b32 s2, v235, 17
	v_readlane_b32 s3, v235, 18
	s_nop 0
	s_and_b64 s[2:3], s[0:1], s[2:3]
	s_mov_b64 exec, s[2:3]
	s_cbranch_execz .LFB_done_k15
	v_mov_b32_e32 v0, 0x23ff0
	ds_read_b32 v2, v0
	ds_read_b32 v3, v0 offset:4
	s_lshl_b32 s2, s96, 8
	s_add_u32 s2, s50, s2
	s_addc_u32 s3, s51, 0
	v_mov_b32_e32 v0, 0x1400
	v_mov_b32_e32 v1, 1
	global_atomic_add v1, v0, v1, s[2:3] sc0
	v_mov_b32_e32 v0, 0x3400
	s_waitcnt vmcnt(0) lgkmcnt(0)
	v_readfirstlane_b32 s5, v1
	v_readfirstlane_b32 s6, v2
	v_readfirstlane_b32 s7, v3
	s_nop 0
	s_add_u32 s5, s5, 1
	s_mul_i32 s6, s6, s4
	s_mul_i32 s4, s7, s4
	s_cmp_lg_u32 s5, s6
	s_mov_b32 s7, 0
	s_cbranch_scc1 .LFB_spin_k15
	buffer_wbl2 sc1
	v_mov_b32_e32 v1, 1
	s_waitcnt vmcnt(0)
	global_atomic_add v0, v1, s[50:51]
